# same stack; dead-proj flag kept in one SGPR (s32) instead of an SGPR pair
# speedup vs baseline: 1.4058x; 1.0011x over previous
.LBB0_316:
	ds_read_b128 v[148:151], v163
	ds_read_b128 v[152:155], v163 offset:1024
	ds_read_b128 v[158:161], v163 offset:2048
	ds_read_b128 v[166:169], v163 offset:3072
	s_add_u32 s10, s8, 0xfff80080
	s_addc_u32 s11, s9, -1
	s_cmp_eq_u32 s57, 28
	s_cselect_b32 s51, s7, s11
	s_cselect_b32 s50, s45, s10
	s_cselect_b32 s59, s53, s56
	s_cselect_b32 s58, s54, s55
	v_lshl_add_u64 v[202:203], s[8:9], 0, v[138:139]
	s_add_i32 m0, s67, 0xc000
	ds_read_b128 v[170:173], v164
	ds_read_b128 v[174:177], v164 offset:1024
	ds_read_b128 v[178:181], v164 offset:2048
	ds_read_b128 v[182:185], v164 offset:3072
	ds_read_b128 v[186:189], v164 offset:4096
	ds_read_b128 v[190:193], v164 offset:5120
	ds_read_b128 v[194:197], v164 offset:6144
	ds_read_b128 v[198:201], v164 offset:7168
	global_load_lds_dwordx4 v[202:203], off
	v_lshl_add_u64 v[202:203], s[8:9], 0, v[140:141]
	s_add_i32 m0, s67, 0xe000
	s_nop 0
	global_load_lds_dwordx4 v[202:203], off
	s_waitcnt lgkmcnt(8)
	s_barrier
	s_waitcnt lgkmcnt(0)
	s_setprio 1
	s_waitcnt lgkmcnt(0)
	v_mfma_f32_16x16x32_bf16 v[124:127], v[148:151], v[170:173], v[124:127]
	v_mfma_f32_16x16x32_bf16 v[120:123], v[158:161], v[170:173], v[120:123]
	v_mfma_f32_16x16x32_bf16 v[108:111], v[148:151], v[178:181], v[108:111]
	v_mfma_f32_16x16x32_bf16 v[104:107], v[158:161], v[178:181], v[104:107]
	v_mfma_f32_16x16x32_bf16 v[92:95], v[148:151], v[186:189], v[92:95]
	v_mfma_f32_16x16x32_bf16 v[88:91], v[158:161], v[186:189], v[88:91]
	v_mfma_f32_16x16x32_bf16 v[76:79], v[148:151], v[194:197], v[76:79]
	v_mfma_f32_16x16x32_bf16 v[72:75], v[158:161], v[194:197], v[72:75]
	v_mfma_f32_16x16x32_bf16 v[124:127], v[152:155], v[174:177], v[124:127]
	v_mfma_f32_16x16x32_bf16 v[120:123], v[166:169], v[174:177], v[120:123]
	v_mfma_f32_16x16x32_bf16 v[108:111], v[152:155], v[182:185], v[108:111]
	v_mfma_f32_16x16x32_bf16 v[104:107], v[166:169], v[182:185], v[104:107]
	v_mfma_f32_16x16x32_bf16 v[92:95], v[152:155], v[190:193], v[92:95]
	v_mfma_f32_16x16x32_bf16 v[88:91], v[166:169], v[190:193], v[88:91]
	v_mfma_f32_16x16x32_bf16 v[76:79], v[152:155], v[198:201], v[76:79]
	v_mfma_f32_16x16x32_bf16 v[72:75], v[166:169], v[198:201], v[72:75]
	s_setprio 0
	s_barrier
	s_add_i32 s10, s82, s66
	v_lshl_add_u64 v[218:219], s[58:59], 0, v[128:129]
	s_mov_b32 m0, s10
	ds_read_b128 v[202:205], v165
	ds_read_b128 v[206:209], v165 offset:1024
	ds_read_b128 v[210:213], v165 offset:2048
	ds_read_b128 v[214:217], v165 offset:3072
	global_load_lds_dwordx4 v[218:219], off
	v_lshl_add_u64 v[220:221], v[218:219], 0, s[12:13]
	s_add_i32 m0, s10, 0x2000
	s_nop 0
	global_load_lds_dwordx4 v[220:221], off
	s_barrier
	s_waitcnt lgkmcnt(0)
	s_setprio 1
	s_waitcnt lgkmcnt(0)
	v_mfma_f32_16x16x32_bf16 v[116:119], v[202:205], v[170:173], v[116:119]
	v_mfma_f32_16x16x32_bf16 v[112:115], v[210:213], v[170:173], v[112:115]
	v_mfma_f32_16x16x32_bf16 v[100:103], v[202:205], v[178:181], v[100:103]
	v_mfma_f32_16x16x32_bf16 v[96:99], v[210:213], v[178:181], v[96:99]
	v_mfma_f32_16x16x32_bf16 v[84:87], v[202:205], v[186:189], v[84:87]
	v_mfma_f32_16x16x32_bf16 v[80:83], v[210:213], v[186:189], v[80:83]
	v_mfma_f32_16x16x32_bf16 v[68:71], v[202:205], v[194:197], v[68:71]
	v_mfma_f32_16x16x32_bf16 v[64:67], v[210:213], v[194:197], v[64:67]
	v_mfma_f32_16x16x32_bf16 v[116:119], v[206:209], v[174:177], v[116:119]
	v_mfma_f32_16x16x32_bf16 v[112:115], v[214:217], v[174:177], v[112:115]
	v_mfma_f32_16x16x32_bf16 v[100:103], v[206:209], v[182:185], v[100:103]
	v_mfma_f32_16x16x32_bf16 v[96:99], v[214:217], v[182:185], v[96:99]
	v_mfma_f32_16x16x32_bf16 v[84:87], v[206:209], v[190:193], v[84:87]
	v_mfma_f32_16x16x32_bf16 v[80:83], v[214:217], v[190:193], v[80:83]
	v_mfma_f32_16x16x32_bf16 v[68:71], v[206:209], v[198:201], v[68:71]
	v_mfma_f32_16x16x32_bf16 v[64:67], v[214:217], v[198:201], v[64:67]
	s_setprio 0
	s_mov_b32 m0, s67
	v_lshl_add_u64 v[220:221], s[50:51], 0, v[130:131]
	s_barrier
	ds_read_b128 v[170:173], v164 offset:16384
	ds_read_b128 v[174:177], v164 offset:17408
	ds_read_b128 v[178:181], v164 offset:18432
	ds_read_b128 v[182:185], v164 offset:19456
	ds_read_b128 v[186:189], v164 offset:20480
	ds_read_b128 v[190:193], v164 offset:21504
	ds_read_b128 v[194:197], v164 offset:22528
	ds_read_b128 v[198:201], v164 offset:23552
	global_load_lds_dwordx4 v[220:221], off
	v_lshl_add_u64 v[222:223], s[50:51], 0, v[132:133]
	s_mov_b32 m0, s68
	s_nop 0
	global_load_lds_dwordx4 v[222:223], off
	s_barrier
	s_waitcnt lgkmcnt(0)
	s_setprio 1
	s_waitcnt lgkmcnt(0)
	v_mfma_f32_16x16x32_bf16 v[60:63], v[148:151], v[170:173], v[60:63]
	v_mfma_f32_16x16x32_bf16 v[56:59], v[158:161], v[170:173], v[56:59]
	v_mfma_f32_16x16x32_bf16 v[44:47], v[148:151], v[178:181], v[44:47]
	v_mfma_f32_16x16x32_bf16 v[40:43], v[158:161], v[178:181], v[40:43]
	v_mfma_f32_16x16x32_bf16 v[28:31], v[148:151], v[186:189], v[28:31]
	v_mfma_f32_16x16x32_bf16 v[24:27], v[158:161], v[186:189], v[24:27]
	v_mfma_f32_16x16x32_bf16 v[12:15], v[148:151], v[194:197], v[12:15]
	v_mfma_f32_16x16x32_bf16 v[8:11], v[158:161], v[194:197], v[8:11]
	v_mfma_f32_16x16x32_bf16 v[60:63], v[152:155], v[174:177], v[60:63]
	v_mfma_f32_16x16x32_bf16 v[56:59], v[166:169], v[174:177], v[56:59]
	v_mfma_f32_16x16x32_bf16 v[44:47], v[152:155], v[182:185], v[44:47]
	v_mfma_f32_16x16x32_bf16 v[40:43], v[166:169], v[182:185], v[40:43]
	v_mfma_f32_16x16x32_bf16 v[28:31], v[152:155], v[190:193], v[28:31]
	v_mfma_f32_16x16x32_bf16 v[24:27], v[166:169], v[190:193], v[24:27]
	v_mfma_f32_16x16x32_bf16 v[12:15], v[152:155], v[198:201], v[12:15]
	v_mfma_f32_16x16x32_bf16 v[8:11], v[166:169], v[198:201], v[8:11]
	s_setprio 0
	s_barrier
	s_add_i32 s10, s83, s66
	v_lshl_add_u64 v[148:149], v[218:219], 0, s[14:15]
	s_mov_b32 m0, s10
	s_nop 0
	global_load_lds_dwordx4 v[148:149], off
	v_lshl_add_u64 v[148:149], v[218:219], 0, s[16:17]
	s_add_i32 m0, s10, 0x2000
	s_nop 0
	global_load_lds_dwordx4 v[148:149], off
	s_waitcnt vmcnt(6)
	s_barrier
	s_setprio 1
	v_mfma_f32_16x16x32_bf16 v[52:55], v[202:205], v[170:173], v[52:55]
	v_mfma_f32_16x16x32_bf16 v[48:51], v[210:213], v[170:173], v[48:51]
	v_mfma_f32_16x16x32_bf16 v[36:39], v[202:205], v[178:181], v[36:39]
	v_mfma_f32_16x16x32_bf16 v[32:35], v[210:213], v[178:181], v[32:35]
	v_mfma_f32_16x16x32_bf16 v[20:23], v[202:205], v[186:189], v[20:23]
	v_mfma_f32_16x16x32_bf16 v[16:19], v[210:213], v[186:189], v[16:19]
	v_mfma_f32_16x16x32_bf16 v[4:7], v[202:205], v[194:197], v[4:7]
	v_mfma_f32_16x16x32_bf16 v[0:3], v[210:213], v[194:197], v[0:3]
	v_mfma_f32_16x16x32_bf16 v[52:55], v[206:209], v[174:177], v[52:55]
	v_mfma_f32_16x16x32_bf16 v[48:51], v[214:217], v[174:177], v[48:51]
	v_mfma_f32_16x16x32_bf16 v[36:39], v[206:209], v[182:185], v[36:39]
	v_mfma_f32_16x16x32_bf16 v[32:35], v[214:217], v[182:185], v[32:35]
	v_mfma_f32_16x16x32_bf16 v[20:23], v[206:209], v[190:193], v[20:23]
	v_mfma_f32_16x16x32_bf16 v[16:19], v[214:217], v[190:193], v[16:19]
	v_mfma_f32_16x16x32_bf16 v[4:7], v[206:209], v[198:201], v[4:7]
	v_mfma_f32_16x16x32_bf16 v[0:3], v[214:217], v[198:201], v[0:3]
	s_setprio 0
	s_add_i32 s10, 0, 0x18000
	v_add_u32_e32 v134, s10, v157
	s_barrier
	ds_read_b128 v[148:151], v134
	ds_read_b128 v[152:155], v134 offset:1024
	ds_read_b128 v[158:161], v134 offset:2048
	ds_read_b128 v[166:169], v134 offset:3072
	s_add_u32 s50, s50, 0x80000
	s_addc_u32 s51, s51, 0
	s_mov_b32 m0, s69
	v_lshl_add_u64 v[202:203], s[50:51], 0, v[130:131]
	ds_read_b128 v[170:173], v164 offset:32768
	ds_read_b128 v[174:177], v164 offset:33792
	ds_read_b128 v[178:181], v164 offset:34816
	ds_read_b128 v[182:185], v164 offset:35840
	ds_read_b128 v[186:189], v164 offset:36864
	ds_read_b128 v[190:193], v164 offset:37888
	ds_read_b128 v[194:197], v164 offset:38912
	ds_read_b128 v[198:201], v164 offset:39936
	global_load_lds_dwordx4 v[202:203], off
	v_lshl_add_u64 v[202:203], s[50:51], 0, v[132:133]
	s_mov_b32 m0, s70
	s_nop 0
	global_load_lds_dwordx4 v[202:203], off
	s_waitcnt lgkmcnt(8)
	s_barrier
	s_waitcnt lgkmcnt(0)
	s_setprio 1
	s_waitcnt lgkmcnt(0)
	v_mfma_f32_16x16x32_bf16 v[124:127], v[148:151], v[170:173], v[124:127]
	v_mfma_f32_16x16x32_bf16 v[120:123], v[158:161], v[170:173], v[120:123]
	v_mfma_f32_16x16x32_bf16 v[108:111], v[148:151], v[178:181], v[108:111]
	v_mfma_f32_16x16x32_bf16 v[104:107], v[158:161], v[178:181], v[104:107]
	v_mfma_f32_16x16x32_bf16 v[92:95], v[148:151], v[186:189], v[92:95]
	v_mfma_f32_16x16x32_bf16 v[88:91], v[158:161], v[186:189], v[88:91]
	v_mfma_f32_16x16x32_bf16 v[76:79], v[148:151], v[194:197], v[76:79]
	v_mfma_f32_16x16x32_bf16 v[72:75], v[158:161], v[194:197], v[72:75]
	v_mfma_f32_16x16x32_bf16 v[124:127], v[152:155], v[174:177], v[124:127]
	v_mfma_f32_16x16x32_bf16 v[120:123], v[166:169], v[174:177], v[120:123]
	v_mfma_f32_16x16x32_bf16 v[108:111], v[152:155], v[182:185], v[108:111]
	v_mfma_f32_16x16x32_bf16 v[104:107], v[166:169], v[182:185], v[104:107]
	v_mfma_f32_16x16x32_bf16 v[92:95], v[152:155], v[190:193], v[92:95]
	v_mfma_f32_16x16x32_bf16 v[88:91], v[166:169], v[190:193], v[88:91]
	v_mfma_f32_16x16x32_bf16 v[76:79], v[152:155], v[198:201], v[76:79]
	v_mfma_f32_16x16x32_bf16 v[72:75], v[166:169], v[198:201], v[72:75]
	s_setprio 0
	s_barrier
	s_add_i32 s11, 0, 0x1c000
	s_add_i32 s10, s10, s66
	v_add_u32_e32 v134, s11, v157
	v_lshl_add_u64 v[224:225], v[218:219], 0, s[26:27]
	s_mov_b32 m0, s10
	ds_read_b128 v[202:205], v134
	ds_read_b128 v[206:209], v134 offset:1024
	ds_read_b128 v[210:213], v134 offset:2048
	ds_read_b128 v[214:217], v134 offset:3072
	global_load_lds_dwordx4 v[224:225], off
	v_lshl_add_u64 v[224:225], v[218:219], 0, s[28:29]
	s_add_i32 m0, s10, 0x2000
	s_nop 0
	global_load_lds_dwordx4 v[224:225], off
	s_barrier
	s_waitcnt lgkmcnt(0)
	s_setprio 1
	s_waitcnt lgkmcnt(0)
	v_mfma_f32_16x16x32_bf16 v[116:119], v[202:205], v[170:173], v[116:119]
	v_mfma_f32_16x16x32_bf16 v[112:115], v[210:213], v[170:173], v[112:115]
	v_mfma_f32_16x16x32_bf16 v[100:103], v[202:205], v[178:181], v[100:103]
	v_mfma_f32_16x16x32_bf16 v[96:99], v[210:213], v[178:181], v[96:99]
	v_mfma_f32_16x16x32_bf16 v[84:87], v[202:205], v[186:189], v[84:87]
	v_mfma_f32_16x16x32_bf16 v[80:83], v[210:213], v[186:189], v[80:83]
	v_mfma_f32_16x16x32_bf16 v[68:71], v[202:205], v[194:197], v[68:71]
	v_mfma_f32_16x16x32_bf16 v[64:67], v[210:213], v[194:197], v[64:67]
	v_mfma_f32_16x16x32_bf16 v[116:119], v[206:209], v[174:177], v[116:119]
	v_mfma_f32_16x16x32_bf16 v[112:115], v[214:217], v[174:177], v[112:115]
	v_mfma_f32_16x16x32_bf16 v[100:103], v[206:209], v[182:185], v[100:103]
	v_mfma_f32_16x16x32_bf16 v[96:99], v[214:217], v[182:185], v[96:99]
	v_mfma_f32_16x16x32_bf16 v[84:87], v[206:209], v[190:193], v[84:87]
	v_mfma_f32_16x16x32_bf16 v[80:83], v[214:217], v[190:193], v[80:83]
	v_mfma_f32_16x16x32_bf16 v[68:71], v[206:209], v[198:201], v[68:71]
	v_mfma_f32_16x16x32_bf16 v[64:67], v[214:217], v[198:201], v[64:67]
	s_setprio 0
	s_mov_b32 m0, s77
	v_lshl_add_u64 v[220:221], v[220:221], 0, s[30:31]
	s_barrier
	ds_read_b128 v[170:173], v164 offset:49152
	ds_read_b128 v[174:177], v164 offset:50176
	ds_read_b128 v[178:181], v164 offset:51200
	ds_read_b128 v[182:185], v164 offset:52224
	ds_read_b128 v[186:189], v164 offset:53248
	ds_read_b128 v[190:193], v164 offset:54272
	ds_read_b128 v[194:197], v164 offset:55296
	ds_read_b128 v[198:201], v164 offset:56320
	global_load_lds_dwordx4 v[220:221], off
	v_lshl_add_u64 v[220:221], v[222:223], 0, s[30:31]
	s_mov_b32 m0, s78
	s_nop 0
	global_load_lds_dwordx4 v[220:221], off
	s_barrier
	s_waitcnt lgkmcnt(0)
	s_setprio 1
	s_waitcnt lgkmcnt(0)
	v_mfma_f32_16x16x32_bf16 v[60:63], v[148:151], v[170:173], v[60:63]
	v_mfma_f32_16x16x32_bf16 v[56:59], v[158:161], v[170:173], v[56:59]
	v_mfma_f32_16x16x32_bf16 v[44:47], v[148:151], v[178:181], v[44:47]
	v_mfma_f32_16x16x32_bf16 v[40:43], v[158:161], v[178:181], v[40:43]
	v_mfma_f32_16x16x32_bf16 v[28:31], v[148:151], v[186:189], v[28:31]
	v_mfma_f32_16x16x32_bf16 v[24:27], v[158:161], v[186:189], v[24:27]
	v_mfma_f32_16x16x32_bf16 v[12:15], v[148:151], v[194:197], v[12:15]
	v_mfma_f32_16x16x32_bf16 v[8:11], v[158:161], v[194:197], v[8:11]
	v_mfma_f32_16x16x32_bf16 v[60:63], v[152:155], v[174:177], v[60:63]
	v_mfma_f32_16x16x32_bf16 v[56:59], v[166:169], v[174:177], v[56:59]
	v_mfma_f32_16x16x32_bf16 v[44:47], v[152:155], v[182:185], v[44:47]
	v_mfma_f32_16x16x32_bf16 v[40:43], v[166:169], v[182:185], v[40:43]
	v_mfma_f32_16x16x32_bf16 v[28:31], v[152:155], v[190:193], v[28:31]
	v_mfma_f32_16x16x32_bf16 v[24:27], v[166:169], v[190:193], v[24:27]
	v_mfma_f32_16x16x32_bf16 v[12:15], v[152:155], v[198:201], v[12:15]
	v_mfma_f32_16x16x32_bf16 v[8:11], v[166:169], v[198:201], v[8:11]
	s_setprio 0
	s_barrier
	s_add_i32 s10, s11, s66
	v_lshl_add_u64 v[148:149], v[218:219], 0, s[34:35]
	s_mov_b32 m0, s10
	s_nop 0
	global_load_lds_dwordx4 v[148:149], off
	v_lshl_add_u64 v[148:149], v[218:219], 0, s[38:39]
	s_add_i32 m0, s10, 0x2000
	s_nop 0
	global_load_lds_dwordx4 v[148:149], off
	s_waitcnt vmcnt(6)
	s_barrier
	s_setprio 1
	v_mfma_f32_16x16x32_bf16 v[52:55], v[202:205], v[170:173], v[52:55]
	v_mfma_f32_16x16x32_bf16 v[48:51], v[210:213], v[170:173], v[48:51]
	v_mfma_f32_16x16x32_bf16 v[36:39], v[202:205], v[178:181], v[36:39]
	v_mfma_f32_16x16x32_bf16 v[32:35], v[210:213], v[178:181], v[32:35]
	v_mfma_f32_16x16x32_bf16 v[20:23], v[202:205], v[186:189], v[20:23]
	v_mfma_f32_16x16x32_bf16 v[16:19], v[210:213], v[186:189], v[16:19]
	v_mfma_f32_16x16x32_bf16 v[4:7], v[202:205], v[194:197], v[4:7]
	v_mfma_f32_16x16x32_bf16 v[0:3], v[210:213], v[194:197], v[0:3]
	v_mfma_f32_16x16x32_bf16 v[52:55], v[206:209], v[174:177], v[52:55]
	v_mfma_f32_16x16x32_bf16 v[48:51], v[214:217], v[174:177], v[48:51]
	v_mfma_f32_16x16x32_bf16 v[36:39], v[206:209], v[182:185], v[36:39]
	v_mfma_f32_16x16x32_bf16 v[32:35], v[214:217], v[182:185], v[32:35]
	v_mfma_f32_16x16x32_bf16 v[20:23], v[206:209], v[190:193], v[20:23]
	v_mfma_f32_16x16x32_bf16 v[16:19], v[214:217], v[190:193], v[16:19]
	v_mfma_f32_16x16x32_bf16 v[4:7], v[206:209], v[198:201], v[4:7]
	v_mfma_f32_16x16x32_bf16 v[0:3], v[214:217], v[198:201], v[0:3]
	s_setprio 0
	s_add_i32 s57, s57, 2
	s_add_u32 s55, s55, 0x8000
	s_addc_u32 s56, s56, 0
	s_add_u32 s8, s8, 0x100
	s_addc_u32 s9, s9, 0
	s_cmp_gt_u32 s57, 29
	s_barrier
	s_cbranch_scc0 .LBB0_316
	s_lshl_b32 s95, s6, 8
	s_and_b32 s8, s52, 0xff
	s_add_i32 s95, s95, s79
	s_and_b32 s6, s52, 0xf8
	s_cmp_eq_u32 s6, 16
	s_cselect_b64 s[56:57], -1, 0
	v_and_b32_e32 v188, 4, v136
	v_mul_u32_u24_e32 v188, 6, v188
	v_mov_b32_e32 v189, 0
	s_mov_b32 s32, 1
	s_cmp_lg_u32 s6, 16
	s_cbranch_scc1 .Lproj_keep
	s_cmpk_ge_u32 s95, 0x4000
	s_cbranch_scc1 .Lproj_keep
	s_mov_b32 s32, 0

.LBB0_330:
	s_or_b64 exec, exec, s[62:63]
	v_mov_b32_e32 v153, v152
	v_mov_b32_e32 v124, v152
	v_mov_b32_e32 v125, v152
	v_pk_mul_f32 v[122:123], v[122:123], v[124:125]
	v_pk_mul_f32 v[120:121], v[120:121], v[152:153]
	v_cvt_pk_bf16_f32 v125, v122, v123
	v_cvt_pk_bf16_f32 v124, v120, v121
	v_mov_b32_e32 v184, v124
	v_mov_b32_e32 v185, v125
	s_nop 1
	v_permlane16_swap_b32_e32 v182, v184
	v_permlane16_swap_b32_e32 v183, v185
	s_cmp_eq_u32 s32, 0
	s_cselect_b64 exec, 0, -1
	v_lshl_add_u64 v[186:187], v[160:161], 0, v[188:189]
	global_store_dwordx4 v[186:187], v[182:185], off
	s_mov_b64 exec, -1
	s_and_saveexec_b64 s[62:63], s[8:9]
	s_cbranch_execz .LBB0_332
	s_ashr_i32 s55, s54, 31
	v_mov_b32_e32 v149, v135
	v_lshl_add_u64 v[126:127], v[148:149], 0, s[54:55]
	v_lshl_add_u64 v[126:127], v[126:127], 2, v[154:155]
	global_store_dwordx4 v[126:127], v[120:123], off offset:64

.LBB0_342:
	s_or_b64 exec, exec, s[62:63]
	s_nop 0
	v_mov_b32_e32 v116, v152
	v_mov_b32_e32 v117, v152
	v_pk_mul_f32 v[114:115], v[114:115], v[116:117]
	v_pk_mul_f32 v[112:113], v[112:113], v[152:153]
	v_cvt_pk_bf16_f32 v117, v114, v115
	v_cvt_pk_bf16_f32 v116, v112, v113
	v_mov_b32_e32 v184, v116
	v_mov_b32_e32 v185, v117
	s_nop 1
	v_permlane16_swap_b32_e32 v182, v184
	v_permlane16_swap_b32_e32 v183, v185
	s_cmp_eq_u32 s32, 0
	s_cselect_b64 exec, 0, -1
	v_lshl_add_u64 v[186:187], v[160:161], 0, v[188:189]
	global_store_dwordx4 v[186:187], v[182:185], off offset:256
	s_mov_b64 exec, -1
	s_and_saveexec_b64 s[62:63], s[8:9]
	s_cbranch_execz .LBB0_344
	s_ashr_i32 s55, s54, 31
	v_mov_b32_e32 v149, v135
	v_lshl_add_u64 v[118:119], v[148:149], 0, s[54:55]
	v_lshl_add_u64 v[118:119], v[118:119], 2, v[154:155]
	global_store_dwordx4 v[118:119], v[112:115], off offset:576

.LBB0_361:
	s_or_b64 exec, exec, s[62:63]
	v_mov_b32_e32 v113, v112
	v_mov_b32_e32 v108, v112
	v_mov_b32_e32 v109, v112
	v_pk_mul_f32 v[106:107], v[106:107], v[108:109]
	v_pk_mul_f32 v[104:105], v[104:105], v[112:113]
	v_cvt_pk_bf16_f32 v109, v106, v107
	v_cvt_pk_bf16_f32 v108, v104, v105
	v_mov_b32_e32 v184, v108
	v_mov_b32_e32 v185, v109
	s_nop 1
	v_permlane16_swap_b32_e32 v182, v184
	v_permlane16_swap_b32_e32 v183, v185
	s_cmp_eq_u32 s32, 0
	s_cselect_b64 exec, 0, -1
	v_lshl_add_u64 v[186:187], v[118:119], 0, v[188:189]
	global_store_dwordx4 v[186:187], v[182:185], off
	s_mov_b64 exec, -1
	s_and_saveexec_b64 s[62:63], s[8:9]
	s_cbranch_execz .LBB0_363
	s_ashr_i32 s55, s54, 31
	v_mov_b32_e32 v149, v135
	v_lshl_add_u64 v[110:111], v[148:149], 0, s[54:55]
	v_lshl_add_u64 v[110:111], v[110:111], 2, v[114:115]
	global_store_dwordx4 v[110:111], v[104:107], off offset:64

.LBB0_373:
	s_or_b64 exec, exec, s[62:63]
	s_nop 0
	v_mov_b32_e32 v100, v112
	v_mov_b32_e32 v101, v112
	v_pk_mul_f32 v[98:99], v[98:99], v[100:101]
	v_pk_mul_f32 v[96:97], v[96:97], v[112:113]
	v_cvt_pk_bf16_f32 v101, v98, v99
	v_cvt_pk_bf16_f32 v100, v96, v97
	v_mov_b32_e32 v184, v100
	v_mov_b32_e32 v185, v101
	s_nop 1
	v_permlane16_swap_b32_e32 v182, v184
	v_permlane16_swap_b32_e32 v183, v185
	s_cmp_eq_u32 s32, 0
	s_cselect_b64 exec, 0, -1
	v_lshl_add_u64 v[186:187], v[118:119], 0, v[188:189]
	global_store_dwordx4 v[186:187], v[182:185], off offset:256
	s_mov_b64 exec, -1
	s_and_saveexec_b64 s[62:63], s[8:9]
	s_cbranch_execz .LBB0_375
	s_ashr_i32 s55, s54, 31
	v_mov_b32_e32 v149, v135
	v_lshl_add_u64 v[102:103], v[148:149], 0, s[54:55]
	v_lshl_add_u64 v[102:103], v[102:103], 2, v[114:115]
	global_store_dwordx4 v[102:103], v[96:99], off offset:576

.LBB0_392:
	s_or_b64 exec, exec, s[62:63]
	v_mov_b32_e32 v97, v96
	v_mov_b32_e32 v92, v96
	v_mov_b32_e32 v93, v96
	v_pk_mul_f32 v[90:91], v[90:91], v[92:93]
	v_pk_mul_f32 v[88:89], v[88:89], v[96:97]
	v_cvt_pk_bf16_f32 v93, v90, v91
	v_cvt_pk_bf16_f32 v92, v88, v89
	v_mov_b32_e32 v184, v92
	v_mov_b32_e32 v185, v93
	s_nop 1
	v_permlane16_swap_b32_e32 v182, v184
	v_permlane16_swap_b32_e32 v183, v185
	s_cmp_eq_u32 s32, 0
	s_cselect_b64 exec, 0, -1
	v_lshl_add_u64 v[186:187], v[102:103], 0, v[188:189]
	global_store_dwordx4 v[186:187], v[182:185], off
	s_mov_b64 exec, -1
	s_and_saveexec_b64 s[62:63], s[8:9]
	s_cbranch_execz .LBB0_394
	s_ashr_i32 s55, s54, 31
	v_mov_b32_e32 v149, v135
	v_lshl_add_u64 v[94:95], v[148:149], 0, s[54:55]
	v_lshl_add_u64 v[94:95], v[94:95], 2, v[98:99]
	global_store_dwordx4 v[94:95], v[88:91], off offset:64

.LBB0_404:
	s_or_b64 exec, exec, s[62:63]
	s_nop 0
	v_mov_b32_e32 v84, v96
	v_mov_b32_e32 v85, v96
	v_pk_mul_f32 v[82:83], v[82:83], v[84:85]
	v_pk_mul_f32 v[80:81], v[80:81], v[96:97]
	v_cvt_pk_bf16_f32 v85, v82, v83
	v_cvt_pk_bf16_f32 v84, v80, v81
	v_mov_b32_e32 v184, v84
	v_mov_b32_e32 v185, v85
	s_nop 1
	v_permlane16_swap_b32_e32 v182, v184
	v_permlane16_swap_b32_e32 v183, v185
	s_cmp_eq_u32 s32, 0
	s_cselect_b64 exec, 0, -1
	v_lshl_add_u64 v[186:187], v[102:103], 0, v[188:189]
	global_store_dwordx4 v[186:187], v[182:185], off offset:256
	s_mov_b64 exec, -1
	s_and_saveexec_b64 s[62:63], s[8:9]
	s_cbranch_execz .LBB0_406
	s_ashr_i32 s55, s54, 31
	v_mov_b32_e32 v149, v135
	v_lshl_add_u64 v[86:87], v[148:149], 0, s[54:55]
	v_lshl_add_u64 v[86:87], v[86:87], 2, v[98:99]
	global_store_dwordx4 v[86:87], v[80:83], off offset:576

.LBB0_423:
	s_or_b64 exec, exec, s[62:63]
	v_mov_b32_e32 v81, v80
	v_mov_b32_e32 v76, v80
	v_mov_b32_e32 v77, v80
	v_pk_mul_f32 v[74:75], v[74:75], v[76:77]
	v_pk_mul_f32 v[72:73], v[72:73], v[80:81]
	v_cvt_pk_bf16_f32 v77, v74, v75
	v_cvt_pk_bf16_f32 v76, v72, v73
	v_mov_b32_e32 v184, v76
	v_mov_b32_e32 v185, v77
	s_nop 1
	v_permlane16_swap_b32_e32 v182, v184
	v_permlane16_swap_b32_e32 v183, v185
	s_cmp_eq_u32 s32, 0
	s_cselect_b64 exec, 0, -1
	v_lshl_add_u64 v[186:187], v[86:87], 0, v[188:189]
	global_store_dwordx4 v[186:187], v[182:185], off
	s_mov_b64 exec, -1
	s_and_saveexec_b64 s[62:63], s[8:9]
	s_cbranch_execz .LBB0_425
	s_ashr_i32 s55, s54, 31
	v_mov_b32_e32 v149, v135
	v_lshl_add_u64 v[78:79], v[148:149], 0, s[54:55]
	v_lshl_add_u64 v[78:79], v[78:79], 2, v[82:83]
	global_store_dwordx4 v[78:79], v[72:75], off offset:64

.LBB0_435:
	s_or_b64 exec, exec, s[62:63]
	s_nop 0
	v_mov_b32_e32 v68, v80
	v_mov_b32_e32 v69, v80
	v_pk_mul_f32 v[66:67], v[66:67], v[68:69]
	v_pk_mul_f32 v[64:65], v[64:65], v[80:81]
	v_cvt_pk_bf16_f32 v69, v66, v67
	v_cvt_pk_bf16_f32 v68, v64, v65
	v_mov_b32_e32 v184, v68
	v_mov_b32_e32 v185, v69
	s_nop 1
	v_permlane16_swap_b32_e32 v182, v184
	v_permlane16_swap_b32_e32 v183, v185
	s_cmp_eq_u32 s32, 0
	s_cselect_b64 exec, 0, -1
	v_lshl_add_u64 v[186:187], v[86:87], 0, v[188:189]
	global_store_dwordx4 v[186:187], v[182:185], off offset:256
	s_mov_b64 exec, -1
	s_and_saveexec_b64 s[62:63], s[8:9]
	s_cbranch_execz .LBB0_437
	s_ashr_i32 s55, s54, 31
	v_mov_b32_e32 v149, v135
	v_lshl_add_u64 v[70:71], v[148:149], 0, s[54:55]
	v_lshl_add_u64 v[70:71], v[70:71], 2, v[82:83]
	global_store_dwordx4 v[70:71], v[64:67], off offset:576

.LBB0_454:
	s_or_b64 exec, exec, s[62:63]
	v_mov_b32_e32 v67, v66
	v_mov_b32_e32 v60, v66
	v_mov_b32_e32 v61, v66
	v_pk_mul_f32 v[58:59], v[58:59], v[60:61]
	v_pk_mul_f32 v[56:57], v[56:57], v[66:67]
	v_cvt_pk_bf16_f32 v61, v58, v59
	v_cvt_pk_bf16_f32 v60, v56, v57
	v_mov_b32_e32 v184, v60
	v_mov_b32_e32 v185, v61
	s_nop 1
	v_permlane16_swap_b32_e32 v182, v184
	v_permlane16_swap_b32_e32 v183, v185
	s_cmp_eq_u32 s32, 0
	s_cselect_b64 exec, 0, -1
	v_lshl_add_u64 v[186:187], v[72:73], 0, v[188:189]
	global_store_dwordx4 v[186:187], v[182:185], off
	s_mov_b64 exec, -1
	s_and_saveexec_b64 s[62:63], s[8:9]
	s_cbranch_execz .LBB0_456
	s_ashr_i32 s55, s54, 31
	v_mov_b32_e32 v149, v135
	v_lshl_add_u64 v[62:63], v[148:149], 0, s[54:55]
	v_lshl_add_u64 v[62:63], v[62:63], 2, v[68:69]
	global_store_dwordx4 v[62:63], v[56:59], off offset:64

.LBB0_466:
	s_or_b64 exec, exec, s[62:63]
	s_nop 0
	v_mov_b32_e32 v52, v66
	v_mov_b32_e32 v53, v66
	v_pk_mul_f32 v[50:51], v[50:51], v[52:53]
	v_pk_mul_f32 v[48:49], v[48:49], v[66:67]
	v_cvt_pk_bf16_f32 v53, v50, v51
	v_cvt_pk_bf16_f32 v52, v48, v49
	v_mov_b32_e32 v184, v52
	v_mov_b32_e32 v185, v53
	s_nop 1
	v_permlane16_swap_b32_e32 v182, v184
	v_permlane16_swap_b32_e32 v183, v185
	s_cmp_eq_u32 s32, 0
	s_cselect_b64 exec, 0, -1
	v_lshl_add_u64 v[186:187], v[72:73], 0, v[188:189]
	global_store_dwordx4 v[186:187], v[182:185], off offset:256
	s_mov_b64 exec, -1
	s_and_saveexec_b64 s[62:63], s[8:9]
	s_cbranch_execz .LBB0_468
	s_ashr_i32 s55, s54, 31
	v_mov_b32_e32 v149, v135
	v_lshl_add_u64 v[54:55], v[148:149], 0, s[54:55]
	v_lshl_add_u64 v[54:55], v[54:55], 2, v[68:69]
	global_store_dwordx4 v[54:55], v[48:51], off offset:576

.LBB0_485:
	s_or_b64 exec, exec, s[62:63]
	v_mov_b32_e32 v49, v48
	v_mov_b32_e32 v44, v48
	v_mov_b32_e32 v45, v48
	v_pk_mul_f32 v[42:43], v[42:43], v[44:45]
	v_pk_mul_f32 v[40:41], v[40:41], v[48:49]
	v_cvt_pk_bf16_f32 v45, v42, v43
	v_cvt_pk_bf16_f32 v44, v40, v41
	v_mov_b32_e32 v184, v44
	v_mov_b32_e32 v185, v45
	s_nop 1
	v_permlane16_swap_b32_e32 v182, v184
	v_permlane16_swap_b32_e32 v183, v185
	s_cmp_eq_u32 s32, 0
	s_cselect_b64 exec, 0, -1
	v_lshl_add_u64 v[186:187], v[54:55], 0, v[188:189]
	global_store_dwordx4 v[186:187], v[182:185], off
	s_mov_b64 exec, -1
	s_and_saveexec_b64 s[62:63], s[8:9]
	s_cbranch_execz .LBB0_487
	s_ashr_i32 s55, s54, 31
	v_mov_b32_e32 v149, v135
	v_lshl_add_u64 v[46:47], v[148:149], 0, s[54:55]
	v_lshl_add_u64 v[46:47], v[46:47], 2, v[50:51]
	global_store_dwordx4 v[46:47], v[40:43], off offset:64

.LBB0_497:
	s_or_b64 exec, exec, s[62:63]
	s_nop 0
	v_mov_b32_e32 v36, v48
	v_mov_b32_e32 v37, v48
	v_pk_mul_f32 v[34:35], v[34:35], v[36:37]
	v_pk_mul_f32 v[32:33], v[32:33], v[48:49]
	v_cvt_pk_bf16_f32 v37, v34, v35
	v_cvt_pk_bf16_f32 v36, v32, v33
	v_mov_b32_e32 v184, v36
	v_mov_b32_e32 v185, v37
	s_nop 1
	v_permlane16_swap_b32_e32 v182, v184
	v_permlane16_swap_b32_e32 v183, v185
	s_cmp_eq_u32 s32, 0
	s_cselect_b64 exec, 0, -1
	v_lshl_add_u64 v[186:187], v[54:55], 0, v[188:189]
	global_store_dwordx4 v[186:187], v[182:185], off offset:256
	s_mov_b64 exec, -1
	s_and_saveexec_b64 s[62:63], s[8:9]
	s_cbranch_execz .LBB0_499
	s_ashr_i32 s55, s54, 31
	v_mov_b32_e32 v149, v135
	v_lshl_add_u64 v[38:39], v[148:149], 0, s[54:55]
	v_lshl_add_u64 v[38:39], v[38:39], 2, v[50:51]
	global_store_dwordx4 v[38:39], v[32:35], off offset:576

.LBB0_516:
	s_or_b64 exec, exec, s[62:63]
	v_mov_b32_e32 v33, v32
	v_mov_b32_e32 v28, v32
	v_mov_b32_e32 v29, v32
	v_pk_mul_f32 v[26:27], v[26:27], v[28:29]
	v_pk_mul_f32 v[24:25], v[24:25], v[32:33]
	v_cvt_pk_bf16_f32 v29, v26, v27
	v_cvt_pk_bf16_f32 v28, v24, v25
	v_mov_b32_e32 v184, v28
	v_mov_b32_e32 v185, v29
	s_nop 1
	v_permlane16_swap_b32_e32 v182, v184
	v_permlane16_swap_b32_e32 v183, v185
	s_cmp_eq_u32 s32, 0
	s_cselect_b64 exec, 0, -1
	v_lshl_add_u64 v[186:187], v[38:39], 0, v[188:189]
	global_store_dwordx4 v[186:187], v[182:185], off
	s_mov_b64 exec, -1
	s_and_saveexec_b64 s[62:63], s[8:9]
	s_cbranch_execz .LBB0_518
	s_ashr_i32 s55, s54, 31
	v_mov_b32_e32 v149, v135
	v_lshl_add_u64 v[30:31], v[148:149], 0, s[54:55]
	v_lshl_add_u64 v[30:31], v[30:31], 2, v[34:35]
	global_store_dwordx4 v[30:31], v[24:27], off offset:64

.LBB0_528:
	s_or_b64 exec, exec, s[62:63]
	s_nop 0
	v_mov_b32_e32 v20, v32
	v_mov_b32_e32 v21, v32
	v_pk_mul_f32 v[18:19], v[18:19], v[20:21]
	v_pk_mul_f32 v[16:17], v[16:17], v[32:33]
	v_cvt_pk_bf16_f32 v21, v18, v19
	v_cvt_pk_bf16_f32 v20, v16, v17
	v_mov_b32_e32 v184, v20
	v_mov_b32_e32 v185, v21
	s_nop 1
	v_permlane16_swap_b32_e32 v182, v184
	v_permlane16_swap_b32_e32 v183, v185
	s_cmp_eq_u32 s32, 0
	s_cselect_b64 exec, 0, -1
	v_lshl_add_u64 v[186:187], v[38:39], 0, v[188:189]
	global_store_dwordx4 v[186:187], v[182:185], off offset:256
	s_mov_b64 exec, -1
	s_and_saveexec_b64 s[62:63], s[8:9]
	s_cbranch_execz .LBB0_530
	s_ashr_i32 s55, s54, 31
	v_mov_b32_e32 v149, v135
	v_lshl_add_u64 v[22:23], v[148:149], 0, s[54:55]
	v_lshl_add_u64 v[22:23], v[22:23], 2, v[34:35]
	global_store_dwordx4 v[22:23], v[16:19], off offset:576

.LBB0_547:
	s_or_b64 exec, exec, s[58:59]
	v_mov_b32_e32 v17, v16
	v_mov_b32_e32 v12, v16
	v_mov_b32_e32 v13, v16
	v_pk_mul_f32 v[10:11], v[10:11], v[12:13]
	v_pk_mul_f32 v[8:9], v[8:9], v[16:17]
	v_cvt_pk_bf16_f32 v13, v10, v11
	v_cvt_pk_bf16_f32 v12, v8, v9
	v_mov_b32_e32 v184, v12
	v_mov_b32_e32 v185, v13
	s_nop 1
	v_permlane16_swap_b32_e32 v182, v184
	v_permlane16_swap_b32_e32 v183, v185
	s_cmp_eq_u32 s32, 0
	s_cselect_b64 exec, 0, -1
	v_lshl_add_u64 v[186:187], v[24:25], 0, v[188:189]
	global_store_dwordx4 v[186:187], v[182:185], off
	s_mov_b64 exec, -1
	s_and_saveexec_b64 s[58:59], s[6:7]
	s_cbranch_execz .LBB0_549
	s_ashr_i32 s55, s54, 31
	v_mov_b32_e32 v149, v135
	v_lshl_add_u64 v[14:15], v[148:149], 0, s[54:55]
	v_lshl_add_u64 v[14:15], v[14:15], 2, v[18:19]
	global_store_dwordx4 v[14:15], v[8:11], off offset:64

.LBB0_559:
	s_or_b64 exec, exec, s[58:59]
	s_nop 0
	v_mov_b32_e32 v4, v16
	v_mov_b32_e32 v5, v16
	v_pk_mul_f32 v[2:3], v[2:3], v[4:5]
	v_pk_mul_f32 v[0:1], v[0:1], v[16:17]
	v_cvt_pk_bf16_f32 v5, v2, v3
	v_cvt_pk_bf16_f32 v4, v0, v1
	v_mov_b32_e32 v184, v4
	v_mov_b32_e32 v185, v5
	s_nop 1
	v_permlane16_swap_b32_e32 v182, v184
	v_permlane16_swap_b32_e32 v183, v185
	s_cmp_eq_u32 s32, 0
	s_cselect_b64 exec, 0, -1
	v_lshl_add_u64 v[186:187], v[24:25], 0, v[188:189]
	global_store_dwordx4 v[186:187], v[182:185], off offset:256
	s_mov_b64 exec, -1
	s_and_saveexec_b64 s[58:59], s[6:7]
	s_cbranch_execz .LBB0_561
	s_ashr_i32 s55, s54, 31
	v_mov_b32_e32 v149, v135
	v_lshl_add_u64 v[6:7], v[148:149], 0, s[54:55]
	v_lshl_add_u64 v[6:7], v[6:7], 2, v[18:19]
	global_store_dwordx4 v[6:7], v[0:3], off offset:576

	.amdhsa_kernel _Z10fwd_kernel6Params
		.amdhsa_group_segment_fixed_size 0
		.amdhsa_private_segment_fixed_size 0
		.amdhsa_kernarg_size 424
		.amdhsa_user_sgpr_count 2
		.amdhsa_user_sgpr_dispatch_ptr 0
		.amdhsa_user_sgpr_queue_ptr 0
		.amdhsa_user_sgpr_kernarg_segment_ptr 1
		.amdhsa_user_sgpr_dispatch_id 0
		.amdhsa_user_sgpr_kernarg_preload_length 0
		.amdhsa_user_sgpr_kernarg_preload_offset 0
		.amdhsa_user_sgpr_private_segment_size 0
		.amdhsa_uses_dynamic_stack 0
		.amdhsa_enable_private_segment 0
		.amdhsa_system_sgpr_workgroup_id_x 1
		.amdhsa_system_sgpr_workgroup_id_y 0
		.amdhsa_system_sgpr_workgroup_id_z 0
		.amdhsa_system_sgpr_workgroup_info 0
		.amdhsa_system_vgpr_workitem_id 2
		.amdhsa_next_free_vgpr 256
		.amdhsa_next_free_sgpr 98
		.amdhsa_accum_offset 256
		.amdhsa_reserve_vcc 1
		.amdhsa_float_round_mode_32 0
		.amdhsa_float_round_mode_16_64 0
		.amdhsa_float_denorm_mode_32 3
		.amdhsa_float_denorm_mode_16_64 3
		.amdhsa_dx10_clamp 1
		.amdhsa_ieee_mode 1
		.amdhsa_fp16_overflow 0
		.amdhsa_tg_split 0
		.amdhsa_exception_fp_ieee_invalid_op 0
		.amdhsa_exception_fp_denorm_src 0
		.amdhsa_exception_fp_ieee_div_zero 0
		.amdhsa_exception_fp_ieee_overflow 0
		.amdhsa_exception_fp_ieee_underflow 0
		.amdhsa_exception_fp_ieee_inexact 0
		.amdhsa_exception_int_div_zero 0
	.end_amdhsa_kernel

amdhsa.kernels:
  - .agpr_count:     0
    .args:
      - .offset:         0
        .size:           168
        .value_kind:     by_value
      - .offset:         168
        .size:           4
        .value_kind:     hidden_block_count_x
      - .offset:         172
        .size:           4
        .value_kind:     hidden_block_count_y
      - .offset:         176
        .size:           4
        .value_kind:     hidden_block_count_z
      - .offset:         180
        .size:           2
        .value_kind:     hidden_group_size_x
      - .offset:         182
        .size:           2
        .value_kind:     hidden_group_size_y
      - .offset:         184
        .size:           2
        .value_kind:     hidden_group_size_z
      - .offset:         186
        .size:           2
        .value_kind:     hidden_remainder_x
      - .offset:         188
        .size:           2
        .value_kind:     hidden_remainder_y
      - .offset:         190
        .size:           2
        .value_kind:     hidden_remainder_z
      - .offset:         208
        .size:           8
        .value_kind:     hidden_global_offset_x
      - .offset:         216
        .size:           8
        .value_kind:     hidden_global_offset_y
      - .offset:         224
        .size:           8
        .value_kind:     hidden_global_offset_z
      - .offset:         232
        .size:           2
        .value_kind:     hidden_grid_dims
      - .offset:         256
        .size:           8
        .value_kind:     hidden_multigrid_sync_arg
      - .offset:         288
        .size:           4
        .value_kind:     hidden_dynamic_lds_size
    .group_segment_fixed_size: 0
    .kernarg_segment_align: 8
    .kernarg_segment_size: 424
    .language:       OpenCL C
    .language_version:
      - 2
      - 0
    .max_flat_workgroup_size: 512
    .name:           _Z10fwd_kernel6Params
    .private_segment_fixed_size: 0
    .sgpr_count:     104
    .sgpr_spill_count: 21
    .symbol:         _Z10fwd_kernel6Params.kd
    .uniform_work_group_size: 1
    .uses_dynamic_stack: false
    .vgpr_count:     256
    .vgpr_spill_count: 0
    .wavefront_size: 64
